# version 97 plus gate|up and in-proj: row-statistics loads issued ahead of the last segment's six next-unit prefetch DMAs; the epilogue waits vmcnt(6) (0 for the last unit) instead of draining the pref
# speedup vs baseline: 1.0043x; 1.0043x over previous
; #define PG8_STAGE(bufoff, gbase, voff) do { _Pragma("unroll") for (int _i = 0; _i < 2; ++_i) \
;         __builtin_amdgcn_global_load_lds((const unsigned*)((const char*)(gbase) + (voff)[_i]), (PG8_LAS unsigned*)(lds + (bufoff) + ldsw + _i * 8192), 16, 0, 0); } while (0)
; #define PG8_LDA(dst, b, h) do { _Pragma("unroll") for (int m = 0; m < 4; ++m) _Pragma("unroll") for (int k = 0; k < 2; ++k) dst[m][k] = *(const PG8_LAS bf16x8*)(lds + PG8_SA(b, h) + aoff + m * 2048 + k * 1024); } while (0)
; #define PG8_MMA(ai, bj, At, Bt) do { __builtin_amdgcn_s_setprio(1); _Pragma("unroll") for (int m = 0; m < 4; ++m) _Pragma("unroll") for (int n = 0; n < 2; ++n) _Pragma("unroll") for (int k = 0; k < 2; ++k) \
;         acc[ai][bj][m][n] = __builtin_amdgcn_mfma_f32_16x16x32_bf16(Bt[n][k], At[m][k], acc[ai][bj][m][n], 0, 0, 0); __builtin_amdgcn_s_setprio(0); } while (0)
; #define PG8_WAIT_V(n) asm volatile("s_waitcnt vmcnt(" #n ")" ::: "memory")
; #define PG8_WAIT_L(n) asm volatile("s_waitcnt lgkmcnt(" #n ")" ::: "memory")
; #define PG8_BAR __builtin_amdgcn_s_barrier()
; #define PG8_SCHED __builtin_amdgcn_sched_barrier(0)
; template <class Epi, class Sched, bool ALIGN_EPI = false, bool SP2 = false>
; __device__ __forceinline__ void gemm_phase(PG8_LAS unsigned char* lds, const Gemm g, const Sched& S, const Epi& E, const int tid_in) {
;     ...
;             PG8_WAIT_V(8); PG8_WAIT_L(0); PG8_BAR; PG8_MMA(0, 0, At, B0); PG8_MMA(0, 1, At, B1); PG8_BAR; PG8_SCHED;
;             PG8_LDA(At, 1, 1); PG8_STAGE(PG8_SB(1, 0), b3, voffB); PG8_STAGE(PG8_SB(1, 1), b3 + hstep, voffB); PG8_STAGE(PG8_SA(1, 0), a3, voffA);
;     __device__ __forceinline__ void operator()(const f32x4 (&acc)[2][2][4][2], const Unit& u, int wr, int wc, int fr, int fq) const {
;     ...
;             for (int m = 0; m < 4; ++m) rs[ai][m] = rowss[row0 + ai * HALF + m * 16];
.Ltsin_join_2:
	s_waitcnt lgkmcnt(0)
	s_barrier
	v_mfma_f32_16x16x32_bf16 v[130:133], v[144:147], v[182:185], v[130:133]
	v_mfma_f32_16x16x32_bf16 v[130:133], v[154:157], v[186:189], v[130:133]
	v_mfma_f32_16x16x32_bf16 v[114:117], v[144:147], v[190:193], v[114:117]
	v_mfma_f32_16x16x32_bf16 v[114:117], v[154:157], v[198:201], v[114:117]
	v_mfma_f32_16x16x32_bf16 v[98:101], v[144:147], v[202:205], v[98:101]
	v_mfma_f32_16x16x32_bf16 v[98:101], v[154:157], v[206:209], v[98:101]
	v_mfma_f32_16x16x32_bf16 v[82:85], v[144:147], v[210:213], v[82:85]
	v_mfma_f32_16x16x32_bf16 v[82:85], v[154:157], v[214:217], v[82:85]
	v_mfma_f32_16x16x32_bf16 v[126:129], v[158:161], v[182:185], v[126:129]
	v_mfma_f32_16x16x32_bf16 v[126:129], v[162:165], v[186:189], v[126:129]
	v_mfma_f32_16x16x32_bf16 v[110:113], v[158:161], v[190:193], v[110:113]
	v_mfma_f32_16x16x32_bf16 v[110:113], v[162:165], v[198:201], v[110:113]
	v_mfma_f32_16x16x32_bf16 v[94:97], v[158:161], v[202:205], v[94:97]
	v_mfma_f32_16x16x32_bf16 v[94:97], v[162:165], v[206:209], v[94:97]
	v_mfma_f32_16x16x32_bf16 v[78:81], v[158:161], v[210:213], v[78:81]
	v_mfma_f32_16x16x32_bf16 v[78:81], v[162:165], v[214:217], v[78:81]
	v_mfma_f32_16x16x32_bf16 v[122:125], v[166:169], v[182:185], v[122:125]
	v_mfma_f32_16x16x32_bf16 v[122:125], v[170:173], v[186:189], v[122:125]
	v_mfma_f32_16x16x32_bf16 v[106:109], v[166:169], v[190:193], v[106:109]
	v_mfma_f32_16x16x32_bf16 v[106:109], v[170:173], v[198:201], v[106:109]
	v_mfma_f32_16x16x32_bf16 v[90:93], v[166:169], v[202:205], v[90:93]
	v_mfma_f32_16x16x32_bf16 v[90:93], v[170:173], v[206:209], v[90:93]
	v_mfma_f32_16x16x32_bf16 v[74:77], v[166:169], v[210:213], v[74:77]
	v_mfma_f32_16x16x32_bf16 v[74:77], v[170:173], v[214:217], v[74:77]
	v_mfma_f32_16x16x32_bf16 v[118:121], v[174:177], v[182:185], v[118:121]
	v_mfma_f32_16x16x32_bf16 v[118:121], v[178:181], v[186:189], v[118:121]
	v_mfma_f32_16x16x32_bf16 v[102:105], v[174:177], v[190:193], v[102:105]
	v_mfma_f32_16x16x32_bf16 v[102:105], v[178:181], v[198:201], v[102:105]
	v_mfma_f32_16x16x32_bf16 v[86:89], v[174:177], v[202:205], v[86:89]
	v_mfma_f32_16x16x32_bf16 v[86:89], v[178:181], v[206:209], v[86:89]
	v_mfma_f32_16x16x32_bf16 v[70:73], v[174:177], v[210:213], v[70:73]
	v_mfma_f32_16x16x32_bf16 v[70:73], v[178:181], v[214:217], v[70:73]
	s_barrier
	s_add_i32 s14, s46, s19
	v_lshl_add_u64 v[148:149], v[148:149], 0, s[28:29]
	s_mov_b32 m0, s14
	ds_read_b128 v[182:185], v152 offset:49152
	ds_read_b128 v[186:189], v152 offset:50176
	ds_read_b128 v[190:193], v152 offset:51200
	ds_read_b128 v[198:201], v152 offset:52224
	ds_read_b128 v[202:205], v152 offset:53248
	ds_read_b128 v[206:209], v152 offset:54272
	ds_read_b128 v[210:213], v152 offset:55296
	ds_read_b128 v[214:217], v152 offset:56320
	s_cmp_lg_u32 s45, 12
	s_cbranch_scc1 .Lrs_in_skip
	v_lshl_add_u32 v246, s38, 8, v5
	v_ashrrev_i32_e32 v247, 31, v246
	v_lshl_add_u64 v[246:247], v[246:247], 2, s[6:7]
	global_load_dword v226, v[246:247], off
	global_load_dword v227, v[246:247], off offset:64
	global_load_dword v228, v[246:247], off offset:128
	global_load_dword v229, v[246:247], off offset:192
	global_load_dword v238, v[246:247], off offset:512
	global_load_dword v239, v[246:247], off offset:576
	global_load_dword v240, v[246:247], off offset:640
	global_load_dword v241, v[246:247], off offset:704
; #define PG8_BAR __builtin_amdgcn_s_barrier()
; template <class Epi, class Sched, bool ALIGN_EPI = false, bool SP2 = false>
; __device__ __forceinline__ void gemm_phase(PG8_LAS unsigned char* lds, const Gemm g, const Sched& S, const Epi& E, const int tid_in) {
;     ...
;             PG8_LDA(At, 1, 1); PG8_STAGE(PG8_SB(1, 0), b3, voffB); PG8_STAGE(PG8_SB(1, 1), b3 + hstep, voffB); PG8_STAGE(PG8_SA(1, 0), a3, voffA);
;             PG8_WAIT_V(8); PG8_WAIT_L(0); PG8_BAR; PG8_MMA(1, 0, At, B0); PG8_MMA(1, 1, At, B1); PG8_BAR; PG8_SCHED;
;             } else {
;             PG8_LDB(B0, 0, 0); PG8_SCHED; PG8_LDA(At, 0, 0); PG8_STAGE(PG8_SA(1, 1), a1 + hstep, voffA);
;             PG8_WAIT_L(8); PG8_BAR; PG8_WAIT_L(0); PG8_MMA(0, 0, At, B0); PG8_BAR; PG8_SCHED;
;             PG8_LDB(B1, 0, 1); PG8_STAGE(PG8_SB(0, 0), b2, voffB);
;             PG8_BAR; PG8_WAIT_L(0); PG8_MMA(0, 1, At, B1); PG8_BAR;
;             PG8_LDA(At, 0, 1); PG8_STAGE(PG8_SA(0, 0), a2, voffA);
;             PG8_BAR; PG8_WAIT_L(0); PG8_MMA(1, 0, At, B0); PG8_BAR; PG8_SCHED;
;             PG8_STAGE(PG8_SB(0, 1), b2 + hstep, voffB);
;             PG8_WAIT_V(6); PG8_BAR; PG8_MMA(1, 1, At, B1); PG8_BAR;
;             PG8_LDB(B0, 1, 0); PG8_SCHED; PG8_LDA(At, 1, 0); PG8_STAGE(PG8_SA(0, 1), a2 + hstep, voffA);
;             PG8_WAIT_L(8); PG8_BAR; PG8_WAIT_L(0); PG8_MMA(0, 0, At, B0); PG8_BAR; PG8_SCHED;
;             PG8_LDB(B1, 1, 1); PG8_STAGE(PG8_SB(1, 0), b3, voffB);
;             PG8_BAR; PG8_WAIT_L(0); PG8_MMA(0, 1, At, B1); PG8_BAR;
;             PG8_LDA(At, 1, 1); PG8_STAGE(PG8_SA(1, 0), a3, voffA);
;             PG8_BAR; PG8_WAIT_L(0); PG8_MMA(1, 0, At, B0); PG8_BAR; PG8_SCHED;
;             PG8_STAGE(PG8_SB(1, 1), b3 + hstep, voffB);
;             PG8_WAIT_V(6); PG8_BAR; PG8_MMA(1, 1, At, B1); PG8_BAR;
;             }
;         }
;         if constexpr (ALIGN_EPI) { if (wr == 0) PG8_BAR; }
;     __device__ __forceinline__ void operator()(const f32x4 (&acc)[2][2][4][2], const Unit& u, int wr, int wc, int fr, int fq) const {
;         const int row0 = u.pm * BM + wr * 64 + fr, col0 = u.pn * BM + wc * 32 + 8 * fq;
;         const bool act = (u.pn == 3) || (u.pn == 4) || (u.pn == 7) || (u.pn == 8);
;         float rs[2][4];
; #pragma unroll
;         for (int ai = 0; ai < 2; ++ai)
; #pragma unroll
;             for (int m = 0; m < 4; ++m) rs[ai][m] = rowss[row0 + ai * HALF + m * 16];
.Lrs_in_skip:
	s_cbranch_vccnz .Ltsin_skip_3
	global_load_lds_dwordx4 v[148:149], off
	s_add_i32 m0, s14, 0x2000
	s_add_u32 s12, s12, 0x40080
	v_lshl_add_u64 v[148:149], v[218:219], 0, s[28:29]
	s_addc_u32 s13, s13, 0
	s_add_i32 s14, s47, s19
	global_load_lds_dwordx4 v[148:149], off
	v_lshl_add_u64 v[148:149], s[12:13], 0, v[134:135]
	s_mov_b32 m0, s14
	s_nop 0
	global_load_lds_dwordx4 v[148:149], off
	v_lshl_add_u64 v[148:149], s[12:13], 0, v[138:139]
	s_add_i32 m0, s14, 0x2000
	s_nop 0
	global_load_lds_dwordx4 v[148:149], off
	v_lshl_add_u64 v[148:149], v[220:221], 0, s[28:29]
	s_mov_b32 m0, s30
	s_nop 0
	global_load_lds_dwordx4 v[148:149], off
	v_lshl_add_u64 v[148:149], v[222:223], 0, s[28:29]
	s_mov_b32 m0, s31
	s_nop 0
	global_load_lds_dwordx4 v[148:149], off
	s_cmp_lg_u32 s45, 12
	s_cbranch_scc1 .Lrsw_in_n
	s_waitcnt vmcnt(16)
	s_branch .Ltsin_join_3
.Lrsw_in_n:
	s_waitcnt vmcnt(8)
	s_branch .Ltsin_join_3
.Ltsin_skip_3:
	s_nop 0
	s_waitcnt vmcnt(8)
.Ltsin_join_3:
	s_waitcnt lgkmcnt(0)
	s_barrier
	v_mfma_f32_16x16x32_bf16 v[66:69], v[144:147], v[182:185], v[66:69]
	v_mfma_f32_16x16x32_bf16 v[66:69], v[154:157], v[186:189], v[66:69]
	v_mfma_f32_16x16x32_bf16 v[50:53], v[144:147], v[190:193], v[50:53]
	v_mfma_f32_16x16x32_bf16 v[50:53], v[154:157], v[198:201], v[50:53]
	v_mfma_f32_16x16x32_bf16 v[34:37], v[144:147], v[202:205], v[34:37]
	v_mfma_f32_16x16x32_bf16 v[34:37], v[154:157], v[206:209], v[34:37]
	v_mfma_f32_16x16x32_bf16 v[18:21], v[144:147], v[210:213], v[18:21]
	v_mfma_f32_16x16x32_bf16 v[18:21], v[154:157], v[214:217], v[18:21]
	v_mfma_f32_16x16x32_bf16 v[62:65], v[158:161], v[182:185], v[62:65]
	v_mfma_f32_16x16x32_bf16 v[62:65], v[162:165], v[186:189], v[62:65]
	v_mfma_f32_16x16x32_bf16 v[46:49], v[158:161], v[190:193], v[46:49]
	v_mfma_f32_16x16x32_bf16 v[46:49], v[162:165], v[198:201], v[46:49]
	v_mfma_f32_16x16x32_bf16 v[30:33], v[158:161], v[202:205], v[30:33]
	v_mfma_f32_16x16x32_bf16 v[30:33], v[162:165], v[206:209], v[30:33]
	v_mfma_f32_16x16x32_bf16 v[14:17], v[158:161], v[210:213], v[14:17]
	v_mfma_f32_16x16x32_bf16 v[14:17], v[162:165], v[214:217], v[14:17]
	v_mfma_f32_16x16x32_bf16 v[58:61], v[166:169], v[182:185], v[58:61]
	v_mfma_f32_16x16x32_bf16 v[58:61], v[170:173], v[186:189], v[58:61]
	v_mfma_f32_16x16x32_bf16 v[42:45], v[166:169], v[190:193], v[42:45]
	v_mfma_f32_16x16x32_bf16 v[42:45], v[170:173], v[198:201], v[42:45]
	v_mfma_f32_16x16x32_bf16 v[26:29], v[166:169], v[202:205], v[26:29]
	v_mfma_f32_16x16x32_bf16 v[26:29], v[170:173], v[206:209], v[26:29]
	v_mfma_f32_16x16x32_bf16 v[10:13], v[166:169], v[210:213], v[10:13]
	v_mfma_f32_16x16x32_bf16 v[10:13], v[170:173], v[214:217], v[10:13]
	v_mfma_f32_16x16x32_bf16 v[54:57], v[174:177], v[182:185], v[54:57]
	v_mfma_f32_16x16x32_bf16 v[54:57], v[178:181], v[186:189], v[54:57]
	v_mfma_f32_16x16x32_bf16 v[38:41], v[174:177], v[190:193], v[38:41]
	v_mfma_f32_16x16x32_bf16 v[38:41], v[178:181], v[198:201], v[38:41]
	v_mfma_f32_16x16x32_bf16 v[22:25], v[174:177], v[202:205], v[22:25]
	v_mfma_f32_16x16x32_bf16 v[22:25], v[178:181], v[206:209], v[22:25]
	v_mfma_f32_16x16x32_bf16 v[6:9], v[174:177], v[210:213], v[6:9]
	v_mfma_f32_16x16x32_bf16 v[6:9], v[178:181], v[214:217], v[6:9]
	s_barrier
	s_add_i32 s45, s45, 2
	s_add_u32 s42, s42, 0x100
	s_addc_u32 s43, s43, 0
	s_add_u32 s25, s25, 0x100
	s_addc_u32 s39, s39, 0
	s_cmp_gt_u32 s45, 13
	s_cbranch_scc0 .LBB0_93
	s_and_b64 vcc, exec, s[8:9]
	s_cbranch_vccz .LBB0_96
	s_barrier
.LBB0_96:
	v_lshl_add_u32 v144, s38, 8, v5
	v_ashrrev_i32_e32 v145, 31, v144
	v_lshl_add_u64 v[146:147], v[144:145], 2, s[6:7]
	s_add_i32 s11, s10, -3
	s_and_b32 s11, s11, -6
	s_cmp_eq_u32 s11, 0
	s_cselect_b64 s[12:13], -1, 0
	s_cmp_lg_u32 s11, 0
	s_mov_b32 s11, 0x800000
	s_mov_b64 vcc, s[36:37]
	s_cbranch_vccz .Lrse_in_last
	s_waitcnt vmcnt(6)
	s_branch .Lrse_in_j

; __device__ __forceinline__ unsigned cvt_pk_bf16(float lo, float hi) { unsigned r; asm volatile("v_cvt_pk_bf16_f32 %0, %1, %2" : "=v"(r) : "v"(lo), "v"(hi)); return r; }
; __device__ __forceinline__ float silu_f(float x) { return x * __builtin_amdgcn_rcpf(1.0f + __expf(-x)); }
; __device__ __forceinline__ float silu_f(float x) { return x * __builtin_amdgcn_rcpf(1.0f + __expf(-x)); }
;     __device__ __forceinline__ void operator()(const f32x4 (&acc)[2][2][4][2], const Unit& u, int wr, int wc, int fr, int fq) const {
;     ...
;             for (int m = 0; m < 4; ++m) {
;                 const int row = row0 + ai * HALF + m * 16;
;                 const float r = rsqrtf(rs[ai][m] * (1.0f / 1024.0f) + RMS_EPS);
; #pragma unroll
;                 for (int bj = 0; bj < 2; ++bj) {
;                     f32x4 a = acc[ai][bj][m][0] * r, b = acc[ai][bj][m][1] * r;
;                     if (act) {
; #pragma unroll
;                         for (int e = 0; e < 4; ++e) { a[e] = silu_f(a[e]); b[e] = silu_f(b[e]); }
;                     }
;                     u32x4 w; w.x = cvt_pk_bf16(a[0], a[1]); w.y = cvt_pk_bf16(a[2], a[3]); w.z = cvt_pk_bf16(b[0], b[1]); w.w = cvt_pk_bf16(b[2], b[3]);
.Lrse_in_j:
	v_fmamk_f32 v146, v226, 0x3a800000, v231
	v_cmp_gt_f32_e32 vcc, s11, v146
	v_mul_f32_e32 v147, 0x4b800000, v146
	s_nop 0
	v_cndmask_b32_e32 v146, v146, v147, vcc
	v_rsq_f32_e32 v146, v146
	s_nop 0
	v_mul_f32_e32 v147, 0x45800000, v146
	v_cndmask_b32_e32 v146, v146, v147, vcc
	v_pk_mul_f32 v[132:133], v[132:133], v[146:147] op_sel_hi:[1,0]
	v_pk_mul_f32 v[130:131], v[130:131], v[146:147] op_sel_hi:[1,0]
	v_pk_mul_f32 v[128:129], v[128:129], v[146:147] op_sel_hi:[1,0]
	v_pk_mul_f32 v[148:149], v[126:127], v[146:147] op_sel_hi:[1,0]
	s_cbranch_scc1 .LBB0_98
	v_mul_f32_e32 v147, 0xbfb8aa3b, v149
	v_exp_f32_e32 v147, v147
	v_mul_f32_e32 v127, 0xbfb8aa3b, v148
	v_exp_f32_e32 v127, v127
	v_mul_f32_e32 v126, 0xbfb8aa3b, v130
	v_add_f32_e32 v147, 1.0, v147
	v_rcp_f32_e32 v161, v147
	v_mul_f32_e32 v147, 0xbfb8aa3b, v132
	v_add_f32_e32 v127, 1.0, v127
	v_exp_f32_e32 v147, v147
	v_rcp_f32_e32 v160, v127
	v_mul_f32_e32 v127, 0xbfb8aa3b, v131
	v_exp_f32_e32 v126, v126
	v_exp_f32_e32 v127, v127
	v_add_f32_e32 v147, 1.0, v147
	v_rcp_f32_e32 v162, v147
	v_mul_f32_e32 v147, 0xbfb8aa3b, v128
	v_add_f32_e32 v126, 1.0, v126
	v_add_f32_e32 v127, 1.0, v127
	v_exp_f32_e32 v147, v147
	v_rcp_f32_e32 v126, v126
	v_rcp_f32_e32 v127, v127
	v_pk_mul_f32 v[148:149], v[148:149], v[160:161]
	v_add_f32_e32 v147, 1.0, v147
	v_rcp_f32_e32 v164, v147
	v_mul_f32_e32 v147, 0xbfb8aa3b, v133
	v_pk_mul_f32 v[130:131], v[130:131], v[126:127]
	v_mul_f32_e32 v126, 0xbfb8aa3b, v129
	v_exp_f32_e32 v147, v147
	v_exp_f32_e32 v126, v126
	v_add_f32_e32 v147, 1.0, v147
	v_add_f32_e32 v126, 1.0, v126
	v_rcp_f32_e32 v163, v147
	v_rcp_f32_e32 v165, v126
	v_pk_mul_f32 v[132:133], v[132:133], v[162:163]
	v_pk_mul_f32 v[128:129], v[128:129], v[164:165]

; #define PG8_STAGE(bufoff, gbase, voff) do { _Pragma("unroll") for (int _i = 0; _i < 2; ++_i) \
;         __builtin_amdgcn_global_load_lds((const unsigned*)((const char*)(gbase) + (voff)[_i]), (PG8_LAS unsigned*)(lds + (bufoff) + ldsw + _i * 8192), 16, 0, 0); } while (0)
; #define PG8_LDA(dst, b, h) do { _Pragma("unroll") for (int m = 0; m < 4; ++m) _Pragma("unroll") for (int k = 0; k < 2; ++k) dst[m][k] = *(const PG8_LAS bf16x8*)(lds + PG8_SA(b, h) + aoff + m * 2048 + k * 1024); } while (0)
; #define PG8_MMA(ai, bj, At, Bt) do { __builtin_amdgcn_s_setprio(1); _Pragma("unroll") for (int m = 0; m < 4; ++m) _Pragma("unroll") for (int n = 0; n < 2; ++n) _Pragma("unroll") for (int k = 0; k < 2; ++k) \
;         acc[ai][bj][m][n] = __builtin_amdgcn_mfma_f32_16x16x32_bf16(Bt[n][k], At[m][k], acc[ai][bj][m][n], 0, 0, 0); __builtin_amdgcn_s_setprio(0); } while (0)
; #define PG8_WAIT_V(n) asm volatile("s_waitcnt vmcnt(" #n ")" ::: "memory")
; #define PG8_WAIT_L(n) asm volatile("s_waitcnt lgkmcnt(" #n ")" ::: "memory")
; #define PG8_BAR __builtin_amdgcn_s_barrier()
; #define PG8_SCHED __builtin_amdgcn_sched_barrier(0)
; template <class Epi, class Sched, bool ALIGN_EPI = false, bool SP2 = false>
; __device__ __forceinline__ void gemm_phase(PG8_LAS unsigned char* lds, const Gemm g, const Sched& S, const Epi& E, const int tid_in) {
;     ...
;             PG8_WAIT_V(8); PG8_WAIT_L(0); PG8_BAR; PG8_MMA(0, 0, At, B0); PG8_MMA(0, 1, At, B1); PG8_BAR; PG8_SCHED;
;             PG8_LDA(At, 1, 1); PG8_STAGE(PG8_SB(1, 0), b3, voffB); PG8_STAGE(PG8_SB(1, 1), b3 + hstep, voffB); PG8_STAGE(PG8_SA(1, 0), a3, voffA);
;     __device__ __forceinline__ void operator()(const f32x4 (&acc)[2][2][4][2], const Unit& u, int wr, int wc, int fr, int fq) const {
;     ...
;             for (int m = 0; m < 4; ++m) rs[ai][m] = rowss[row0 + ai * HALF + m * 16];
.Ltsgu_join_2:
	s_waitcnt lgkmcnt(0)
	s_barrier
	v_mfma_f32_16x16x32_bf16 v[130:133], v[150:153], v[182:185], v[130:133]
	v_mfma_f32_16x16x32_bf16 v[130:133], v[154:157], v[186:189], v[130:133]
	v_mfma_f32_16x16x32_bf16 v[114:117], v[150:153], v[190:193], v[114:117]
	v_mfma_f32_16x16x32_bf16 v[114:117], v[154:157], v[198:201], v[114:117]
	v_mfma_f32_16x16x32_bf16 v[98:101], v[150:153], v[202:205], v[98:101]
	v_mfma_f32_16x16x32_bf16 v[98:101], v[154:157], v[206:209], v[98:101]
	v_mfma_f32_16x16x32_bf16 v[82:85], v[150:153], v[210:213], v[82:85]
	v_mfma_f32_16x16x32_bf16 v[82:85], v[154:157], v[214:217], v[82:85]
	v_mfma_f32_16x16x32_bf16 v[126:129], v[158:161], v[182:185], v[126:129]
	v_mfma_f32_16x16x32_bf16 v[126:129], v[162:165], v[186:189], v[126:129]
	v_mfma_f32_16x16x32_bf16 v[106:109], v[158:161], v[190:193], v[106:109]
	v_mfma_f32_16x16x32_bf16 v[106:109], v[162:165], v[198:201], v[106:109]
	v_mfma_f32_16x16x32_bf16 v[94:97], v[158:161], v[202:205], v[94:97]
	v_mfma_f32_16x16x32_bf16 v[94:97], v[162:165], v[206:209], v[94:97]
	v_mfma_f32_16x16x32_bf16 v[78:81], v[158:161], v[210:213], v[78:81]
	v_mfma_f32_16x16x32_bf16 v[78:81], v[162:165], v[214:217], v[78:81]
	v_mfma_f32_16x16x32_bf16 v[122:125], v[166:169], v[182:185], v[122:125]
	v_mfma_f32_16x16x32_bf16 v[122:125], v[170:173], v[186:189], v[122:125]
	v_mfma_f32_16x16x32_bf16 v[110:113], v[166:169], v[190:193], v[110:113]
	v_mfma_f32_16x16x32_bf16 v[110:113], v[170:173], v[198:201], v[110:113]
	v_mfma_f32_16x16x32_bf16 v[90:93], v[166:169], v[202:205], v[90:93]
	v_mfma_f32_16x16x32_bf16 v[90:93], v[170:173], v[206:209], v[90:93]
	v_mfma_f32_16x16x32_bf16 v[74:77], v[166:169], v[210:213], v[74:77]
	v_mfma_f32_16x16x32_bf16 v[74:77], v[170:173], v[214:217], v[74:77]
	v_mfma_f32_16x16x32_bf16 v[118:121], v[174:177], v[182:185], v[118:121]
	v_mfma_f32_16x16x32_bf16 v[118:121], v[178:181], v[186:189], v[118:121]
	v_mfma_f32_16x16x32_bf16 v[102:105], v[174:177], v[190:193], v[102:105]
	v_mfma_f32_16x16x32_bf16 v[102:105], v[178:181], v[198:201], v[102:105]
	v_mfma_f32_16x16x32_bf16 v[86:89], v[174:177], v[202:205], v[86:89]
	v_mfma_f32_16x16x32_bf16 v[86:89], v[178:181], v[206:209], v[86:89]
	v_mfma_f32_16x16x32_bf16 v[70:73], v[174:177], v[210:213], v[70:73]
	v_mfma_f32_16x16x32_bf16 v[70:73], v[178:181], v[214:217], v[70:73]
	s_barrier
	s_add_i32 s14, s46, s17
	v_lshl_add_u64 v[144:145], v[144:145], 0, s[28:29]
	s_mov_b32 m0, s14
	ds_read_b128 v[182:185], v148 offset:49152
	ds_read_b128 v[186:189], v148 offset:50176
	ds_read_b128 v[190:193], v148 offset:51200
	ds_read_b128 v[198:201], v148 offset:52224
	ds_read_b128 v[202:205], v148 offset:53248
	ds_read_b128 v[206:209], v148 offset:54272
	ds_read_b128 v[210:213], v148 offset:55296
	ds_read_b128 v[214:217], v148 offset:56320
	s_cmp_lg_u32 s45, 12
	s_cbranch_scc1 .Lrs_gu_skip
	v_lshl_add_u32 v246, s40, 8, v5
	v_ashrrev_i32_e32 v247, 31, v246
	v_lshl_add_u64 v[246:247], v[246:247], 2, s[6:7]
	global_load_dword v226, v[246:247], off
	global_load_dword v227, v[246:247], off offset:64
	global_load_dword v228, v[246:247], off offset:128
	global_load_dword v229, v[246:247], off offset:192
	global_load_dword v238, v[246:247], off offset:512
	global_load_dword v239, v[246:247], off offset:576
	global_load_dword v240, v[246:247], off offset:640
	global_load_dword v241, v[246:247], off offset:704
.Lrs_gu_skip:
	s_cbranch_vccnz .Ltsgu_skip_3
	global_load_lds_dwordx4 v[144:145], off
	s_add_i32 m0, s14, 0x2000
	s_add_u32 s12, s12, 0x40080
	v_lshl_add_u64 v[144:145], v[218:219], 0, s[28:29]
	s_addc_u32 s13, s13, 0
	s_add_i32 s14, s47, s17
	global_load_lds_dwordx4 v[144:145], off
	v_lshl_add_u64 v[144:145], s[12:13], 0, v[136:137]
	s_mov_b32 m0, s14
	s_nop 0
	global_load_lds_dwordx4 v[144:145], off
	v_lshl_add_u64 v[144:145], s[12:13], 0, v[2:3]
	s_add_i32 m0, s14, 0x2000
	s_nop 0
	global_load_lds_dwordx4 v[144:145], off
	v_lshl_add_u64 v[144:145], v[220:221], 0, s[28:29]
	s_mov_b32 m0, s26
	s_nop 0
	global_load_lds_dwordx4 v[144:145], off
	v_lshl_add_u64 v[144:145], v[222:223], 0, s[28:29]
	s_mov_b32 m0, s27
	s_nop 0
	global_load_lds_dwordx4 v[144:145], off
	s_cmp_lg_u32 s45, 12
	s_cbranch_scc1 .Lrsw_gu_n
	s_waitcnt vmcnt(16)
	s_branch .Ltsgu_join_3

; #define PG8_BAR __builtin_amdgcn_s_barrier()
; template <class Epi, class Sched, bool ALIGN_EPI = false, bool SP2 = false>
; __device__ __forceinline__ void gemm_phase(PG8_LAS unsigned char* lds, const Gemm g, const Sched& S, const Epi& E, const int tid_in) {
;     ...
;             PG8_WAIT_V(8); PG8_WAIT_L(0); PG8_BAR; PG8_MMA(1, 0, At, B0); PG8_MMA(1, 1, At, B1); PG8_BAR; PG8_SCHED;
;             } else {
;             PG8_LDB(B0, 0, 0); PG8_SCHED; PG8_LDA(At, 0, 0); PG8_STAGE(PG8_SA(1, 1), a1 + hstep, voffA);
;             PG8_WAIT_L(8); PG8_BAR; PG8_WAIT_L(0); PG8_MMA(0, 0, At, B0); PG8_BAR; PG8_SCHED;
;             PG8_LDB(B1, 0, 1); PG8_STAGE(PG8_SB(0, 0), b2, voffB);
;             PG8_BAR; PG8_WAIT_L(0); PG8_MMA(0, 1, At, B1); PG8_BAR;
;             PG8_LDA(At, 0, 1); PG8_STAGE(PG8_SA(0, 0), a2, voffA);
;             PG8_BAR; PG8_WAIT_L(0); PG8_MMA(1, 0, At, B0); PG8_BAR; PG8_SCHED;
;             PG8_STAGE(PG8_SB(0, 1), b2 + hstep, voffB);
;             PG8_WAIT_V(6); PG8_BAR; PG8_MMA(1, 1, At, B1); PG8_BAR;
;             PG8_LDB(B0, 1, 0); PG8_SCHED; PG8_LDA(At, 1, 0); PG8_STAGE(PG8_SA(0, 1), a2 + hstep, voffA);
;             PG8_WAIT_L(8); PG8_BAR; PG8_WAIT_L(0); PG8_MMA(0, 0, At, B0); PG8_BAR; PG8_SCHED;
;             PG8_LDB(B1, 1, 1); PG8_STAGE(PG8_SB(1, 0), b3, voffB);
;             PG8_BAR; PG8_WAIT_L(0); PG8_MMA(0, 1, At, B1); PG8_BAR;
;             PG8_LDA(At, 1, 1); PG8_STAGE(PG8_SA(1, 0), a3, voffA);
;             PG8_BAR; PG8_WAIT_L(0); PG8_MMA(1, 0, At, B0); PG8_BAR; PG8_SCHED;
;             PG8_STAGE(PG8_SB(1, 1), b3 + hstep, voffB);
;             PG8_WAIT_V(6); PG8_BAR; PG8_MMA(1, 1, At, B1); PG8_BAR;
;             }
;         }
;         if constexpr (ALIGN_EPI) { if (wr == 0) PG8_BAR; }
;     __device__ __forceinline__ void operator()(const f32x4 (&acc)[2][2][4][2], const Unit& u, int wr, int wc, int fr, int fq) const {
;     ...
;                 const int row = row0 + ai * HALF + m * 16;
;                 const float ms = rs[ai][m] * (1.0f / 1024.0f) + RMS_EPS, c1 = -1.4426950408889634f * rsqrtf(ms);
;                 const f32x4 g0 = acc[ai][0][m][0], g1 = acc[ai][0][m][1], u0 = acc[ai][1][m][0], u1 = acc[ai][1][m][1];
;                 const f32x4 t0 = g0 * c1, t1 = g1 * c1; f32x4 e0, e1, i0, i1;
; #pragma unroll
;                 for (int e = 0; e < 4; ++e) { e0[e] = __builtin_amdgcn_exp2f(t0[e]); e1[e] = __builtin_amdgcn_exp2f(t1[e]); }
.Ltsgu_join_3:
	s_waitcnt lgkmcnt(0)
	s_barrier
	v_mfma_f32_16x16x32_bf16 v[66:69], v[150:153], v[182:185], v[66:69]
	v_mfma_f32_16x16x32_bf16 v[66:69], v[154:157], v[186:189], v[66:69]
	v_mfma_f32_16x16x32_bf16 v[50:53], v[150:153], v[190:193], v[50:53]
	v_mfma_f32_16x16x32_bf16 v[50:53], v[154:157], v[198:201], v[50:53]
	v_mfma_f32_16x16x32_bf16 v[34:37], v[150:153], v[202:205], v[34:37]
	v_mfma_f32_16x16x32_bf16 v[34:37], v[154:157], v[206:209], v[34:37]
	v_mfma_f32_16x16x32_bf16 v[18:21], v[150:153], v[210:213], v[18:21]
	v_mfma_f32_16x16x32_bf16 v[18:21], v[154:157], v[214:217], v[18:21]
	v_mfma_f32_16x16x32_bf16 v[62:65], v[158:161], v[182:185], v[62:65]
	v_mfma_f32_16x16x32_bf16 v[62:65], v[162:165], v[186:189], v[62:65]
	v_mfma_f32_16x16x32_bf16 v[46:49], v[158:161], v[190:193], v[46:49]
	v_mfma_f32_16x16x32_bf16 v[46:49], v[162:165], v[198:201], v[46:49]
	v_mfma_f32_16x16x32_bf16 v[30:33], v[158:161], v[202:205], v[30:33]
	v_mfma_f32_16x16x32_bf16 v[30:33], v[162:165], v[206:209], v[30:33]
	v_mfma_f32_16x16x32_bf16 v[14:17], v[158:161], v[210:213], v[14:17]
	v_mfma_f32_16x16x32_bf16 v[14:17], v[162:165], v[214:217], v[14:17]
	v_mfma_f32_16x16x32_bf16 v[58:61], v[166:169], v[182:185], v[58:61]
	v_mfma_f32_16x16x32_bf16 v[58:61], v[170:173], v[186:189], v[58:61]
	v_mfma_f32_16x16x32_bf16 v[42:45], v[166:169], v[190:193], v[42:45]
	v_mfma_f32_16x16x32_bf16 v[42:45], v[170:173], v[198:201], v[42:45]
	v_mfma_f32_16x16x32_bf16 v[26:29], v[166:169], v[202:205], v[26:29]
	v_mfma_f32_16x16x32_bf16 v[26:29], v[170:173], v[206:209], v[26:29]
	v_mfma_f32_16x16x32_bf16 v[10:13], v[166:169], v[210:213], v[10:13]
	v_mfma_f32_16x16x32_bf16 v[10:13], v[170:173], v[214:217], v[10:13]
	v_mfma_f32_16x16x32_bf16 v[54:57], v[174:177], v[182:185], v[54:57]
	v_mfma_f32_16x16x32_bf16 v[54:57], v[178:181], v[186:189], v[54:57]
	v_mfma_f32_16x16x32_bf16 v[38:41], v[174:177], v[190:193], v[38:41]
	v_mfma_f32_16x16x32_bf16 v[38:41], v[178:181], v[198:201], v[38:41]
	v_mfma_f32_16x16x32_bf16 v[22:25], v[174:177], v[202:205], v[22:25]
	v_mfma_f32_16x16x32_bf16 v[22:25], v[178:181], v[206:209], v[22:25]
	v_mfma_f32_16x16x32_bf16 v[6:9], v[174:177], v[210:213], v[6:9]
	v_mfma_f32_16x16x32_bf16 v[6:9], v[178:181], v[214:217], v[6:9]
	s_barrier
	s_add_i32 s45, s45, 2
	s_add_u32 s10, s10, 0x100
	s_addc_u32 s11, s11, 0
	s_add_u32 s43, s43, 0x100
	s_addc_u32 s44, s44, 0
	s_cmp_gt_u32 s45, 13
	s_cbranch_scc0 .LBB0_154
	s_and_b64 vcc, exec, s[8:9]
	s_cbranch_vccz .LBB0_157
	s_barrier
.LBB0_157:
	v_lshl_add_u32 v144, s40, 8, v5
	v_ashrrev_i32_e32 v145, 31, v144
	v_lshl_add_u64 v[162:163], v[144:145], 2, s[6:7]
	s_mov_b32 s12, 0x800000
	v_pk_mul_f32 v[124:125], v[132:133], v[124:125]
	v_pk_mul_f32 v[122:123], v[130:131], v[122:123]
	v_pk_mul_f32 v[118:119], v[126:127], v[118:119]
	v_lshl_or_b32 v162, s31, 7, v147
	v_pk_mul_f32 v[120:121], v[128:129], v[120:121]
	v_ashrrev_i32_e32 v163, 31, v162
	s_movk_i32 s13, 0x1600
	v_pk_mul_f32 v[104:105], v[108:109], v[104:105]
	v_pk_mul_f32 v[102:103], v[106:107], v[102:103]
	v_or_b32_e32 v160, 16, v144
	v_pk_mul_f32 v[112:113], v[116:117], v[112:113]
	v_pk_mul_f32 v[110:111], v[114:115], v[110:111]
	v_pk_mul_f32 v[90:91], v[98:99], v[90:91]
	v_or_b32_e32 v158, 32, v144
	v_pk_mul_f32 v[92:93], v[100:101], v[92:93]
	v_pk_mul_f32 v[88:89], v[96:97], v[88:89]
	v_pk_mul_f32 v[86:87], v[94:95], v[86:87]
	v_pk_mul_f32 v[74:75], v[82:83], v[74:75]
	v_or_b32_e32 v156, 48, v144
	v_pk_mul_f32 v[76:77], v[84:85], v[76:77]
	v_pk_mul_f32 v[72:73], v[80:81], v[72:73]
	v_pk_mul_f32 v[70:71], v[78:79], v[70:71]
	v_pk_mul_f32 v[58:59], v[66:67], v[58:59]
	v_add_u32_e32 v154, 0x80, v144
	v_pk_mul_f32 v[60:61], v[68:69], v[60:61]
	v_pk_mul_f32 v[56:57], v[64:65], v[56:57]
	v_pk_mul_f32 v[54:55], v[62:63], v[54:55]
	v_pk_mul_f32 v[42:43], v[50:51], v[42:43]
	v_add_u32_e32 v152, 0x90, v144
	v_pk_mul_f32 v[44:45], v[52:53], v[44:45]
	v_pk_mul_f32 v[40:41], v[48:49], v[40:41]
	v_pk_mul_f32 v[38:39], v[46:47], v[38:39]
	v_pk_mul_f32 v[26:27], v[34:35], v[26:27]
	v_add_u32_e32 v150, 0xa0, v144
	v_pk_mul_f32 v[28:29], v[36:37], v[28:29]
	v_pk_mul_f32 v[24:25], v[32:33], v[24:25]
	v_pk_mul_f32 v[22:23], v[30:31], v[22:23]
	v_pk_mul_f32 v[10:11], v[18:19], v[10:11]
	v_add_u32_e32 v145, 0xb0, v144
	v_pk_mul_f32 v[12:13], v[20:21], v[12:13]
	v_pk_mul_f32 v[8:9], v[16:17], v[8:9]
	v_pk_mul_f32 v[6:7], v[14:15], v[6:7]
	s_mov_b64 vcc, s[36:37]
	s_cbranch_vccz .Lrse_gu_last
	s_waitcnt vmcnt(6)
	s_branch .Lrse_gu_j

; __device__ __forceinline__ unsigned cvt2_bf16(float lo, float hi) { const f32x2n v = {lo, hi}; return __builtin_bit_cast(unsigned, __builtin_convertvector(v, bf16x2n)); }
;     __device__ __forceinline__ void operator()(const f32x4 (&acc)[2][2][4][2], const Unit& u, int wr, int wc, int fr, int fq) const {
;     ...
;         for (int ai = 0; ai < 2; ++ai)
; #pragma unroll
;             for (int m = 0; m < 4; ++m) {
;                 const int row = row0 + ai * HALF + m * 16;
;                 const float ms = rs[ai][m] * (1.0f / 1024.0f) + RMS_EPS, c1 = -1.4426950408889634f * rsqrtf(ms);
;                 const f32x4 g0 = acc[ai][0][m][0], g1 = acc[ai][0][m][1], u0 = acc[ai][1][m][0], u1 = acc[ai][1][m][1];
;                 const f32x4 t0 = g0 * c1, t1 = g1 * c1; f32x4 e0, e1, i0, i1;
; #pragma unroll
;                 for (int e = 0; e < 4; ++e) { e0[e] = __builtin_amdgcn_exp2f(t0[e]); e1[e] = __builtin_amdgcn_exp2f(t1[e]); }
;                 const f32x4 d0 = e0 * ms + ms, d1 = e1 * ms + ms;
; #pragma unroll
;                 for (int e = 0; e < 4; ++e) { i0[e] = __builtin_amdgcn_rcpf(d0[e]); i1[e] = __builtin_amdgcn_rcpf(d1[e]); }
;                 const f32x4 h0 = (g0 * u0) * i0, h1 = (g1 * u1) * i1;
;                 u32x4 w; w.x = cvt2_bf16(h0[0], h0[1]); w.y = cvt2_bf16(h0[2], h0[3]); w.z = cvt2_bf16(h1[0], h1[1]); w.w = cvt2_bf16(h1[2], h1[3]);
;                 *(u32x4*)(H + (size_t)row * ldh + col0) = w;
.Lrse_gu_j:
	v_fmamk_f32 v164, v226, 0x3a800000, v231
	v_cmp_gt_f32_e32 vcc, s12, v164
	v_mul_f32_e32 v161, 0x4b800000, v164
	s_nop 0
	v_cndmask_b32_e32 v161, v164, v161, vcc
	v_rsq_f32_e32 v161, v161
	s_nop 0
	v_mul_f32_e32 v165, 0x45800000, v161
	v_cndmask_b32_e32 v161, v161, v165, vcc
	v_mul_f32_e32 v166, 0xbfb8aa3b, v161
	v_pk_mul_f32 v[168:169], v[132:133], v[166:167] op_sel_hi:[1,0]
	v_pk_mul_f32 v[170:171], v[130:131], v[166:167] op_sel_hi:[1,0]
	v_pk_mul_f32 v[172:173], v[128:129], v[166:167] op_sel_hi:[1,0]
	v_pk_mul_f32 v[166:167], v[126:127], v[166:167] op_sel_hi:[1,0]
	v_exp_f32_e32 v170, v170
	v_exp_f32_e32 v166, v166
	v_exp_f32_e32 v171, v171
	v_exp_f32_e32 v167, v167
	v_exp_f32_e32 v168, v168
	v_exp_f32_e32 v172, v172
	v_exp_f32_e32 v169, v169
	v_exp_f32_e32 v173, v173
	v_pk_fma_f32 v[170:171], v[164:165], v[170:171], v[164:165] op_sel_hi:[0,1,0]
	v_pk_fma_f32 v[168:169], v[164:165], v[168:169], v[164:165] op_sel_hi:[0,1,0]
	v_pk_fma_f32 v[172:173], v[164:165], v[172:173], v[164:165] op_sel_hi:[0,1,0]
	v_pk_fma_f32 v[164:165], v[164:165], v[166:167], v[164:165] op_sel_hi:[0,1,0]
	v_rcp_f32_e32 v166, v170
	v_rcp_f32_e32 v164, v164
	v_rcp_f32_e32 v167, v171
	v_rcp_f32_e32 v165, v165
	v_rcp_f32_e32 v168, v168
	v_rcp_f32_e32 v169, v169
	v_rcp_f32_e32 v170, v172
	v_rcp_f32_e32 v171, v173
	v_pk_mul_f32 v[122:123], v[122:123], v[166:167]
	v_pk_mul_f32 v[124:125], v[124:125], v[168:169]
	v_pk_mul_f32 v[118:119], v[118:119], v[164:165]
	v_pk_mul_f32 v[120:121], v[120:121], v[170:171]
	v_cvt_pk_bf16_f32 v122, v122, v123
	v_cvt_pk_bf16_f32 v123, v124, v125
	v_cvt_pk_bf16_f32 v124, v118, v119
	v_mov_b64_e32 v[118:119], s[86:87]
	v_cvt_pk_bf16_f32 v125, v120, v121
	v_mad_i64_i32 v[126:127], s[10:11], v144, s13, v[118:119]
	v_lshlrev_b64 v[120:121], 1, v[162:163]
	v_lshl_add_u64 v[126:127], v[126:127], 0, v[120:121]
	global_store_dwordx4 v[126:127], v[122:125], off
	s_nop 1
	v_fmamk_f32 v122, v227, 0x3a800000, v231
	v_cmp_gt_f32_e32 vcc, s12, v122
	v_mul_f32_e32 v123, 0x4b800000, v122
	s_nop 0
	v_cndmask_b32_e32 v123, v122, v123, vcc
	v_rsq_f32_e32 v123, v123
	s_nop 0
	v_mul_f32_e32 v124, 0x45800000, v123
	v_cndmask_b32_e32 v123, v123, v124, vcc
	v_mul_f32_e32 v124, 0xbfb8aa3b, v123
	v_pk_mul_f32 v[126:127], v[116:117], v[124:125] op_sel_hi:[1,0]
	v_pk_mul_f32 v[128:129], v[114:115], v[124:125] op_sel_hi:[1,0]
	v_pk_mul_f32 v[130:131], v[108:109], v[124:125] op_sel_hi:[1,0]
	v_pk_mul_f32 v[124:125], v[106:107], v[124:125] op_sel_hi:[1,0]
	v_exp_f32_e32 v128, v128
	v_exp_f32_e32 v124, v124
	v_exp_f32_e32 v129, v129
	v_exp_f32_e32 v125, v125
	v_exp_f32_e32 v126, v126
	v_exp_f32_e32 v130, v130
	v_exp_f32_e32 v127, v127
	v_exp_f32_e32 v131, v131
	v_pk_fma_f32 v[132:133], v[122:123], v[126:127], v[122:123] op_sel_hi:[0,1,0]
	v_pk_fma_f32 v[126:127], v[122:123], v[128:129], v[122:123] op_sel_hi:[0,1,0]
	v_pk_fma_f32 v[130:131], v[122:123], v[130:131], v[122:123] op_sel_hi:[0,1,0]
	v_pk_fma_f32 v[122:123], v[122:123], v[124:125], v[122:123] op_sel_hi:[0,1,0]
	v_rcp_f32_e32 v122, v122
	v_rcp_f32_e32 v123, v123
	v_rcp_f32_e32 v124, v130
	v_rcp_f32_e32 v125, v131
	v_rcp_f32_e32 v126, v126
	v_rcp_f32_e32 v127, v127
	v_rcp_f32_e32 v128, v132
	v_rcp_f32_e32 v129, v133
	v_pk_mul_f32 v[106:107], v[104:105], v[124:125]
	v_pk_mul_f32 v[104:105], v[102:103], v[122:123]
	v_pk_mul_f32 v[110:111], v[110:111], v[126:127]
	v_pk_mul_f32 v[112:113], v[112:113], v[128:129]
	v_cvt_pk_bf16_f32 v104, v104, v105
	v_cvt_pk_bf16_f32 v105, v106, v107
	v_mad_i64_i32 v[106:107], s[10:11], v160, s13, v[118:119]
	v_cvt_pk_bf16_f32 v102, v110, v111
	v_cvt_pk_bf16_f32 v103, v112, v113
	v_lshl_add_u64 v[106:107], v[106:107], 0, v[120:121]
	global_store_dwordx4 v[106:107], v[102:105], off
	s_nop 1
	v_fmamk_f32 v102, v228, 0x3a800000, v231
	v_cmp_gt_f32_e32 vcc, s12, v102
	v_mul_f32_e32 v103, 0x4b800000, v102
	s_nop 0
	v_cndmask_b32_e32 v103, v102, v103, vcc
	v_rsq_f32_e32 v103, v103
	s_nop 0
	v_mul_f32_e32 v104, 0x45800000, v103
	v_cndmask_b32_e32 v103, v103, v104, vcc
	v_mul_f32_e32 v104, 0xbfb8aa3b, v103
	v_pk_mul_f32 v[108:109], v[98:99], v[104:105] op_sel_hi:[1,0]
	v_pk_mul_f32 v[106:107], v[100:101], v[104:105] op_sel_hi:[1,0]
	v_pk_mul_f32 v[110:111], v[96:97], v[104:105] op_sel_hi:[1,0]
	v_pk_mul_f32 v[104:105], v[94:95], v[104:105] op_sel_hi:[1,0]
	v_exp_f32_e32 v108, v108
	v_exp_f32_e32 v109, v109
	v_exp_f32_e32 v104, v104
	v_exp_f32_e32 v105, v105
	v_exp_f32_e32 v106, v106
	v_exp_f32_e32 v110, v110
	v_exp_f32_e32 v107, v107
	v_exp_f32_e32 v111, v111
	v_pk_fma_f32 v[108:109], v[102:103], v[108:109], v[102:103] op_sel_hi:[0,1,0]
	v_pk_fma_f32 v[106:107], v[102:103], v[106:107], v[102:103] op_sel_hi:[0,1,0]
	v_pk_fma_f32 v[110:111], v[102:103], v[110:111], v[102:103] op_sel_hi:[0,1,0]
	v_pk_fma_f32 v[102:103], v[102:103], v[104:105], v[102:103] op_sel_hi:[0,1,0]
	v_rcp_f32_e32 v104, v108
	v_rcp_f32_e32 v105, v109
	v_rcp_f32_e32 v102, v102
	v_rcp_f32_e32 v103, v103
	v_rcp_f32_e32 v106, v106
	v_rcp_f32_e32 v108, v110
	v_rcp_f32_e32 v107, v107
	v_rcp_f32_e32 v109, v111
	v_pk_mul_f32 v[90:91], v[90:91], v[104:105]
	v_pk_mul_f32 v[92:93], v[92:93], v[106:107]
	v_pk_mul_f32 v[94:95], v[88:89], v[108:109]
	v_pk_mul_f32 v[88:89], v[86:87], v[102:103]
	v_cvt_pk_bf16_f32 v86, v90, v91
	v_mad_i64_i32 v[90:91], s[10:11], v158, s13, v[118:119]
	v_cvt_pk_bf16_f32 v87, v92, v93
	v_cvt_pk_bf16_f32 v88, v88, v89
	v_cvt_pk_bf16_f32 v89, v94, v95
	v_lshl_add_u64 v[90:91], v[90:91], 0, v[120:121]
	global_store_dwordx4 v[90:91], v[86:89], off
	s_nop 1
	v_fmamk_f32 v86, v229, 0x3a800000, v231
	v_cmp_gt_f32_e32 vcc, s12, v86
	v_mul_f32_e32 v87, 0x4b800000, v86
	s_nop 0
	v_cndmask_b32_e32 v87, v86, v87, vcc
; __device__ __forceinline__ unsigned cvt2_bf16(float lo, float hi) { const f32x2n v = {lo, hi}; return __builtin_bit_cast(unsigned, __builtin_convertvector(v, bf16x2n)); }
;     __device__ __forceinline__ void operator()(const f32x4 (&acc)[2][2][4][2], const Unit& u, int wr, int wc, int fr, int fq) const {
;     ...
;             for (int m = 0; m < 4; ++m) {
;                 const int row = row0 + ai * HALF + m * 16;
;                 const float ms = rs[ai][m] * (1.0f / 1024.0f) + RMS_EPS, c1 = -1.4426950408889634f * rsqrtf(ms);
;                 const f32x4 g0 = acc[ai][0][m][0], g1 = acc[ai][0][m][1], u0 = acc[ai][1][m][0], u1 = acc[ai][1][m][1];
;                 const f32x4 t0 = g0 * c1, t1 = g1 * c1; f32x4 e0, e1, i0, i1;
; #pragma unroll
;                 for (int e = 0; e < 4; ++e) { e0[e] = __builtin_amdgcn_exp2f(t0[e]); e1[e] = __builtin_amdgcn_exp2f(t1[e]); }
;                 const f32x4 d0 = e0 * ms + ms, d1 = e1 * ms + ms;
; #pragma unroll
;                 for (int e = 0; e < 4; ++e) { i0[e] = __builtin_amdgcn_rcpf(d0[e]); i1[e] = __builtin_amdgcn_rcpf(d1[e]); }
;                 const f32x4 h0 = (g0 * u0) * i0, h1 = (g1 * u1) * i1;
;                 u32x4 w; w.x = cvt2_bf16(h0[0], h0[1]); w.y = cvt2_bf16(h0[2], h0[3]); w.z = cvt2_bf16(h1[0], h1[1]); w.w = cvt2_bf16(h1[2], h1[3]);
;                 *(u32x4*)(H + (size_t)row * ldh + col0) = w;
	v_rsq_f32_e32 v87, v87
	s_nop 0
	v_mul_f32_e32 v88, 0x45800000, v87
	v_cndmask_b32_e32 v87, v87, v88, vcc
	v_mul_f32_e32 v88, 0xbfb8aa3b, v87
	v_pk_mul_f32 v[92:93], v[82:83], v[88:89] op_sel_hi:[1,0]
	v_pk_mul_f32 v[90:91], v[84:85], v[88:89] op_sel_hi:[1,0]
	v_pk_mul_f32 v[94:95], v[80:81], v[88:89] op_sel_hi:[1,0]
	v_pk_mul_f32 v[88:89], v[78:79], v[88:89] op_sel_hi:[1,0]
	v_exp_f32_e32 v92, v92
	v_exp_f32_e32 v93, v93
	v_exp_f32_e32 v88, v88
	v_exp_f32_e32 v89, v89
	v_exp_f32_e32 v90, v90
	v_exp_f32_e32 v94, v94
	v_exp_f32_e32 v91, v91
	v_exp_f32_e32 v95, v95
	v_pk_fma_f32 v[92:93], v[86:87], v[92:93], v[86:87] op_sel_hi:[0,1,0]
	v_pk_fma_f32 v[90:91], v[86:87], v[90:91], v[86:87] op_sel_hi:[0,1,0]
	v_pk_fma_f32 v[94:95], v[86:87], v[94:95], v[86:87] op_sel_hi:[0,1,0]
	v_pk_fma_f32 v[86:87], v[86:87], v[88:89], v[86:87] op_sel_hi:[0,1,0]
	v_rcp_f32_e32 v88, v92
	v_rcp_f32_e32 v89, v93
	v_rcp_f32_e32 v86, v86
	v_rcp_f32_e32 v87, v87
	v_rcp_f32_e32 v90, v90
	v_rcp_f32_e32 v92, v94
	v_rcp_f32_e32 v91, v91
	v_rcp_f32_e32 v93, v95
	v_pk_mul_f32 v[74:75], v[74:75], v[88:89]
	v_pk_mul_f32 v[76:77], v[76:77], v[90:91]
	v_pk_mul_f32 v[78:79], v[72:73], v[92:93]
	v_pk_mul_f32 v[72:73], v[70:71], v[86:87]
	v_cvt_pk_bf16_f32 v70, v74, v75
	v_mad_i64_i32 v[74:75], s[10:11], v156, s13, v[118:119]
	v_cvt_pk_bf16_f32 v71, v76, v77
	v_cvt_pk_bf16_f32 v72, v72, v73
	v_cvt_pk_bf16_f32 v73, v78, v79
	v_lshl_add_u64 v[74:75], v[74:75], 0, v[120:121]
	global_store_dwordx4 v[74:75], v[70:73], off
	s_nop 1
	v_fmamk_f32 v70, v238, 0x3a800000, v231
	v_cmp_gt_f32_e32 vcc, s12, v70
	v_mul_f32_e32 v71, 0x4b800000, v70
	s_nop 0
	v_cndmask_b32_e32 v71, v70, v71, vcc
	v_rsq_f32_e32 v71, v71
	s_nop 0
	v_mul_f32_e32 v72, 0x45800000, v71
	v_cndmask_b32_e32 v71, v71, v72, vcc
	v_mul_f32_e32 v72, 0xbfb8aa3b, v71
	v_pk_mul_f32 v[76:77], v[66:67], v[72:73] op_sel_hi:[1,0]
	v_pk_mul_f32 v[74:75], v[68:69], v[72:73] op_sel_hi:[1,0]
	v_pk_mul_f32 v[78:79], v[64:65], v[72:73] op_sel_hi:[1,0]
	v_pk_mul_f32 v[72:73], v[62:63], v[72:73] op_sel_hi:[1,0]
	v_exp_f32_e32 v76, v76
	v_exp_f32_e32 v77, v77
	v_exp_f32_e32 v72, v72
	v_exp_f32_e32 v73, v73
	v_exp_f32_e32 v74, v74
	v_exp_f32_e32 v78, v78
	v_exp_f32_e32 v75, v75
	v_exp_f32_e32 v79, v79
	v_pk_fma_f32 v[76:77], v[70:71], v[76:77], v[70:71] op_sel_hi:[0,1,0]
	v_pk_fma_f32 v[74:75], v[70:71], v[74:75], v[70:71] op_sel_hi:[0,1,0]
	v_pk_fma_f32 v[78:79], v[70:71], v[78:79], v[70:71] op_sel_hi:[0,1,0]
	v_pk_fma_f32 v[70:71], v[70:71], v[72:73], v[70:71] op_sel_hi:[0,1,0]
	v_rcp_f32_e32 v72, v76
	v_rcp_f32_e32 v73, v77
	v_rcp_f32_e32 v70, v70
	v_rcp_f32_e32 v71, v71
	v_rcp_f32_e32 v74, v74
	v_rcp_f32_e32 v76, v78
	v_rcp_f32_e32 v75, v75
	v_rcp_f32_e32 v77, v79
	v_pk_mul_f32 v[58:59], v[58:59], v[72:73]
	v_pk_mul_f32 v[60:61], v[60:61], v[74:75]
	v_pk_mul_f32 v[62:63], v[56:57], v[76:77]
	v_pk_mul_f32 v[56:57], v[54:55], v[70:71]
	v_cvt_pk_bf16_f32 v54, v58, v59
	v_mad_i64_i32 v[58:59], s[10:11], v154, s13, v[118:119]
	v_cvt_pk_bf16_f32 v55, v60, v61
	v_cvt_pk_bf16_f32 v56, v56, v57
	v_cvt_pk_bf16_f32 v57, v62, v63
	v_lshl_add_u64 v[58:59], v[58:59], 0, v[120:121]
	global_store_dwordx4 v[58:59], v[54:57], off
	s_nop 1
	v_fmamk_f32 v54, v239, 0x3a800000, v231
	v_cmp_gt_f32_e32 vcc, s12, v54
	v_mul_f32_e32 v55, 0x4b800000, v54
	s_nop 0
	v_cndmask_b32_e32 v55, v54, v55, vcc
	v_rsq_f32_e32 v55, v55
	s_nop 0
	v_mul_f32_e32 v56, 0x45800000, v55
	v_cndmask_b32_e32 v55, v55, v56, vcc
	v_mul_f32_e32 v56, 0xbfb8aa3b, v55
	v_pk_mul_f32 v[60:61], v[50:51], v[56:57] op_sel_hi:[1,0]
	v_pk_mul_f32 v[58:59], v[52:53], v[56:57] op_sel_hi:[1,0]
	v_pk_mul_f32 v[62:63], v[48:49], v[56:57] op_sel_hi:[1,0]
	v_pk_mul_f32 v[56:57], v[46:47], v[56:57] op_sel_hi:[1,0]
	v_exp_f32_e32 v60, v60
	v_exp_f32_e32 v61, v61
	v_exp_f32_e32 v56, v56
	v_exp_f32_e32 v57, v57
	v_exp_f32_e32 v58, v58
	v_exp_f32_e32 v62, v62
	v_exp_f32_e32 v59, v59
	v_exp_f32_e32 v63, v63
	v_pk_fma_f32 v[60:61], v[54:55], v[60:61], v[54:55] op_sel_hi:[0,1,0]
	v_pk_fma_f32 v[58:59], v[54:55], v[58:59], v[54:55] op_sel_hi:[0,1,0]
	v_pk_fma_f32 v[62:63], v[54:55], v[62:63], v[54:55] op_sel_hi:[0,1,0]
	v_pk_fma_f32 v[54:55], v[54:55], v[56:57], v[54:55] op_sel_hi:[0,1,0]
; #define PG8_BAR __builtin_amdgcn_s_barrier()
; __device__ __forceinline__ unsigned cvt2_bf16(float lo, float hi) { const f32x2n v = {lo, hi}; return __builtin_bit_cast(unsigned, __builtin_convertvector(v, bf16x2n)); }
; template <class Epi, class Sched, bool ALIGN_EPI = false, bool SP2 = false>
; __device__ __forceinline__ void gemm_phase(PG8_LAS unsigned char* lds, const Gemm g, const Sched& S, const Epi& E, const int tid_in) {
;     ...
;         if (!has_next) break;
; #pragma unroll
;         for (int a = 0; a < 2; ++a)
; #pragma unroll
;             for (int b = 0; b < 2; ++b)
; #pragma unroll
;                 for (int m = 0; m < 4; ++m)
; #pragma unroll
;                     for (int n = 0; n < 2; ++n) acc[a][b][m][n] = (f32x4){0.f, 0.f, 0.f, 0.f};
;         cur = nxt; cA = nA; cB = nB; ++ui;
;         if constexpr (ALIGN_EPI) { if (wr == 1) PG8_BAR; }
;     __device__ __forceinline__ void operator()(const f32x4 (&acc)[2][2][4][2], const Unit& u, int wr, int wc, int fr, int fq) const {
;     ...
;             for (int m = 0; m < 4; ++m) {
;                 const int row = row0 + ai * HALF + m * 16;
;                 const float ms = rs[ai][m] * (1.0f / 1024.0f) + RMS_EPS, c1 = -1.4426950408889634f * rsqrtf(ms);
;                 const f32x4 g0 = acc[ai][0][m][0], g1 = acc[ai][0][m][1], u0 = acc[ai][1][m][0], u1 = acc[ai][1][m][1];
;                 const f32x4 t0 = g0 * c1, t1 = g1 * c1; f32x4 e0, e1, i0, i1;
; #pragma unroll
;                 for (int e = 0; e < 4; ++e) { e0[e] = __builtin_amdgcn_exp2f(t0[e]); e1[e] = __builtin_amdgcn_exp2f(t1[e]); }
;                 const f32x4 d0 = e0 * ms + ms, d1 = e1 * ms + ms;
; #pragma unroll
;                 for (int e = 0; e < 4; ++e) { i0[e] = __builtin_amdgcn_rcpf(d0[e]); i1[e] = __builtin_amdgcn_rcpf(d1[e]); }
;                 const f32x4 h0 = (g0 * u0) * i0, h1 = (g1 * u1) * i1;
;                 u32x4 w; w.x = cvt2_bf16(h0[0], h0[1]); w.y = cvt2_bf16(h0[2], h0[3]); w.z = cvt2_bf16(h1[0], h1[1]); w.w = cvt2_bf16(h1[2], h1[3]);
;                 *(u32x4*)(H + (size_t)row * ldh + col0) = w;
	v_rcp_f32_e32 v56, v60
	v_rcp_f32_e32 v57, v61
	v_rcp_f32_e32 v54, v54
	v_rcp_f32_e32 v55, v55
	v_rcp_f32_e32 v58, v58
	v_rcp_f32_e32 v60, v62
	v_rcp_f32_e32 v59, v59
	v_rcp_f32_e32 v61, v63
	v_pk_mul_f32 v[42:43], v[42:43], v[56:57]
	v_pk_mul_f32 v[44:45], v[44:45], v[58:59]
	v_pk_mul_f32 v[46:47], v[40:41], v[60:61]
	v_pk_mul_f32 v[40:41], v[38:39], v[54:55]
	v_cvt_pk_bf16_f32 v38, v42, v43
	v_mad_i64_i32 v[42:43], s[10:11], v152, s13, v[118:119]
	v_cvt_pk_bf16_f32 v39, v44, v45
	v_cvt_pk_bf16_f32 v40, v40, v41
	v_cvt_pk_bf16_f32 v41, v46, v47
	v_lshl_add_u64 v[42:43], v[42:43], 0, v[120:121]
	global_store_dwordx4 v[42:43], v[38:41], off
	s_nop 1
	v_fmamk_f32 v38, v240, 0x3a800000, v231
	v_cmp_gt_f32_e32 vcc, s12, v38
	v_mul_f32_e32 v39, 0x4b800000, v38
	s_nop 0
	v_cndmask_b32_e32 v39, v38, v39, vcc
	v_rsq_f32_e32 v39, v39
	s_nop 0
	v_mul_f32_e32 v40, 0x45800000, v39
	v_cndmask_b32_e32 v39, v39, v40, vcc
	v_mul_f32_e32 v40, 0xbfb8aa3b, v39
	v_pk_mul_f32 v[44:45], v[34:35], v[40:41] op_sel_hi:[1,0]
	v_pk_mul_f32 v[42:43], v[36:37], v[40:41] op_sel_hi:[1,0]
	v_pk_mul_f32 v[46:47], v[32:33], v[40:41] op_sel_hi:[1,0]
	v_pk_mul_f32 v[40:41], v[30:31], v[40:41] op_sel_hi:[1,0]
	v_exp_f32_e32 v44, v44
	v_exp_f32_e32 v45, v45
	v_exp_f32_e32 v40, v40
	v_exp_f32_e32 v41, v41
	v_exp_f32_e32 v42, v42
	v_exp_f32_e32 v46, v46
	v_exp_f32_e32 v43, v43
	v_exp_f32_e32 v47, v47
	v_pk_fma_f32 v[44:45], v[38:39], v[44:45], v[38:39] op_sel_hi:[0,1,0]
	v_pk_fma_f32 v[42:43], v[38:39], v[42:43], v[38:39] op_sel_hi:[0,1,0]
	v_pk_fma_f32 v[46:47], v[38:39], v[46:47], v[38:39] op_sel_hi:[0,1,0]
	v_pk_fma_f32 v[38:39], v[38:39], v[40:41], v[38:39] op_sel_hi:[0,1,0]
	v_rcp_f32_e32 v40, v44
	v_rcp_f32_e32 v41, v45
	v_rcp_f32_e32 v38, v38
	v_rcp_f32_e32 v39, v39
	v_rcp_f32_e32 v42, v42
	v_rcp_f32_e32 v44, v46
	v_rcp_f32_e32 v43, v43
	v_rcp_f32_e32 v45, v47
	v_pk_mul_f32 v[26:27], v[26:27], v[40:41]
	v_pk_mul_f32 v[28:29], v[28:29], v[42:43]
	v_pk_mul_f32 v[30:31], v[24:25], v[44:45]
	v_pk_mul_f32 v[24:25], v[22:23], v[38:39]
	v_cvt_pk_bf16_f32 v22, v26, v27
	v_mad_i64_i32 v[26:27], s[10:11], v150, s13, v[118:119]
	v_cvt_pk_bf16_f32 v23, v28, v29
	v_cvt_pk_bf16_f32 v24, v24, v25
	v_cvt_pk_bf16_f32 v25, v30, v31
	v_lshl_add_u64 v[26:27], v[26:27], 0, v[120:121]
	global_store_dwordx4 v[26:27], v[22:25], off
	s_nop 1
	v_fmamk_f32 v22, v241, 0x3a800000, v231
	v_cmp_gt_f32_e32 vcc, s12, v22
	v_mul_f32_e32 v23, 0x4b800000, v22
	s_nop 0
	v_cndmask_b32_e32 v23, v22, v23, vcc
	v_rsq_f32_e32 v23, v23
	s_nop 0
	v_mul_f32_e32 v24, 0x45800000, v23
	v_cndmask_b32_e32 v23, v23, v24, vcc
	v_mul_f32_e32 v24, 0xbfb8aa3b, v23
	v_pk_mul_f32 v[28:29], v[18:19], v[24:25] op_sel_hi:[1,0]
	v_pk_mul_f32 v[26:27], v[20:21], v[24:25] op_sel_hi:[1,0]
	v_pk_mul_f32 v[30:31], v[16:17], v[24:25] op_sel_hi:[1,0]
	v_pk_mul_f32 v[24:25], v[14:15], v[24:25] op_sel_hi:[1,0]
	v_exp_f32_e32 v28, v28
	v_exp_f32_e32 v29, v29
	v_exp_f32_e32 v24, v24
	v_exp_f32_e32 v25, v25
	v_exp_f32_e32 v26, v26
	v_exp_f32_e32 v30, v30
	v_exp_f32_e32 v27, v27
	v_exp_f32_e32 v31, v31
	v_pk_fma_f32 v[28:29], v[22:23], v[28:29], v[22:23] op_sel_hi:[0,1,0]
	s_andn2_b64 vcc, exec, s[36:37]
	v_pk_fma_f32 v[26:27], v[22:23], v[26:27], v[22:23] op_sel_hi:[0,1,0]
	v_pk_fma_f32 v[30:31], v[22:23], v[30:31], v[22:23] op_sel_hi:[0,1,0]
	v_pk_fma_f32 v[22:23], v[22:23], v[24:25], v[22:23] op_sel_hi:[0,1,0]
	v_rcp_f32_e32 v24, v28
	v_rcp_f32_e32 v25, v29
	v_rcp_f32_e32 v22, v22
	v_rcp_f32_e32 v23, v23
	v_rcp_f32_e32 v26, v26
	v_rcp_f32_e32 v28, v30
	v_rcp_f32_e32 v27, v27
	v_rcp_f32_e32 v29, v31
	v_pk_mul_f32 v[10:11], v[10:11], v[24:25]
	v_pk_mul_f32 v[12:13], v[12:13], v[26:27]
	v_pk_mul_f32 v[14:15], v[8:9], v[28:29]
	v_pk_mul_f32 v[8:9], v[6:7], v[22:23]
	v_cvt_pk_bf16_f32 v6, v10, v11
	v_mad_i64_i32 v[10:11], s[10:11], v145, s13, v[118:119]
	v_cvt_pk_bf16_f32 v7, v12, v13
	v_cvt_pk_bf16_f32 v8, v8, v9
	v_cvt_pk_bf16_f32 v9, v14, v15
	v_lshl_add_u64 v[10:11], v[10:11], 0, v[120:121]
	s_mov_b64 s[10:11], -1
	global_store_dwordx4 v[10:11], v[6:9], off
	s_cbranch_vccnz .LBB0_150
	s_andn2_b64 vcc, exec, s[4:5]
	s_cbranch_vccnz .LBB0_149
	s_barrier
	s_branch .LBB0_149
